# adds pipelined K-loops for FFN-up s=1 (layer 0) and the w_in GEMM
# speedup vs baseline: 1.0440x; 1.0440x over previous
; template <int EPI, int MI>
; DI void gemm_tile(const GemmDesc& g, int tm, int tn, char* smem) {
;     ...
;   const int tid = get_tid(), lane = tid & 63, wave = tid >> 6, r = lane & 31, hh = lane >> 5;
;   const int wm = wave >> 1, wn = wave & 1;
;   const int m0 = tm * BM, n0 = tn * 128;
;   const int nk = g.K >> 6;
;   f32x16 acc[MI][2];
; #pragma unroll
;   for (int a = 0; a < MI; ++a)
; #pragma unroll
;     for (int b = 0; b < 2; ++b)
; #pragma unroll
;       for (int i = 0; i < 16; ++i) acc[a][b][i] = 0.f;
;   const int srow = tid >> 3;
;   const int schunk = (tid & 7) ^ ((srow & 7) ^ ((srow >> 3) & 3));
;     ...
;   const int rowA = wm * (32 * MI) + r, rowB = wn * 64 + r;
;   const int hk = hh ^ ((r & 7) ^ ((r >> 3) & 3));
;     ...
;   G_GLDS(0, 0);
;   asm volatile("s_waitcnt vmcnt(0)" ::: "memory");
;   __syncthreads();
; template <int EPI, int MI>
; DI void gemm_phase(const GemmDesc& g, char* smem, int vb, int nvb) {
;     ...
;   for (int q = start; q < local; q += step) {
;     const int mg = q / per;
;     const int rem = q - mg * per;
;     const int tn = rem / PM;
;     const int tm = mbase + mg * PM + (rem - tn * PM);
.LBB0_371:
	s_abs_i32 s1, s47
	s_mul_hi_u32 s4, s1, s45
	s_mul_i32 s5, s4, s43
	s_sub_i32 s1, s1, s5
	s_ashr_i32 s0, s47, 31
	s_add_i32 s5, s4, 1
	s_sub_i32 s15, s1, s43
	s_cmp_ge_u32 s1, s43
	s_cselect_b32 s4, s5, s4
	s_cselect_b32 s1, s15, s1
	s_add_i32 s5, s4, 1
	s_cmp_ge_u32 s1, s43
	s_cselect_b32 s1, s5, s4
	s_xor_b32 s1, s1, s0
	s_sub_i32 s4, s1, s0
	s_mul_i32 s5, s4, s43
	s_sub_i32 s5, s47, s5
	s_abs_i32 s16, s5
	v_readlane_b32 s17, v219, 46
	s_mul_hi_u32 s17, s16, s17
	v_readlane_b32 s38, v218, 32
	s_mul_i32 s18, s17, s38
	s_sub_i32 s16, s16, s18
	s_ashr_i32 s15, s5, 31
	s_add_i32 s18, s17, 1
	s_sub_i32 s19, s16, s38
	s_cmp_ge_u32 s16, s38
	s_cselect_b32 s17, s18, s17
	s_cselect_b32 s16, s19, s16
	s_add_i32 s18, s17, 1
	s_cmp_ge_u32 s16, s38
	s_cselect_b32 s16, s18, s17
	s_xor_b32 s16, s16, s15
	s_sub_i32 s17, s16, s15
	s_sub_i32 s18, s4, s17
	v_mov_b32_e32 v97, v132
	s_mul_i32 s18, s18, s38
	s_add_i32 s5, s5, s54
	s_add_i32 s48, s5, s18
	v_ashrrev_i32_e32 v0, 7, v97
	v_and_b32_e32 v1, 7, v97
	v_mul_lo_u32 v115, v0, s6
	v_lshrrev_b32_e32 v0, 3, v97
	s_mulk_i32 s48, 0xc0
	s_waitcnt vmcnt(8)
	v_bfe_u32 v109, v97, 5, 1
	v_ashrrev_i32_e32 v8, 3, v97
	v_bitop3_b32 v0, v0, v1, 3 bitop3:0x6c
	v_bfe_u32 v2, v97, 6, 2
	v_xor_b32_e32 v3, v8, v97
	v_xor_b32_e32 v10, v0, v109
	v_add_u32_e32 v0, s48, v8
	s_lshl_b32 s49, s17, 7
	v_bitop3_b32 v2, v3, v2, 7 bitop3:0x6c
	v_ashrrev_i32_e32 v1, 31, v0
	v_readlane_b32 s18, v223, 59
	v_lshlrev_b64 v[0:1], 11, v[0:1]
	v_readlane_b32 s19, v223, 60
	v_lshlrev_b32_e32 v98, 4, v2
	v_add_u32_e32 v2, s49, v8
	v_lshlrev_b32_e32 v120, 4, v97
	v_lshl_add_u64 v[0:1], s[18:19], 0, v[0:1]
	v_ashrrev_i32_e32 v3, 31, v2
	v_readlane_b32 s18, v221, 16
	v_add_u32_e32 v121, 0, v120
	v_mov_b32_e32 v99, v96
	v_lshlrev_b64 v[2:3], 11, v[2:3]
	v_readlane_b32 s19, v221, 17
	v_readfirstlane_b32 s5, v121
	v_add_u32_e32 v122, 0x1000, v121
	v_lshl_add_u64 v[0:1], v[0:1], 0, v[98:99]
	v_lshl_add_u64 v[4:5], s[18:19], 0, v[2:3]
	s_mov_b32 m0, s5
	s_mov_b64 s[18:19], 0x10000
	v_readfirstlane_b32 s5, v122
	v_add_u32_e32 v123, 0x2000, v121
	global_load_lds_dwordx4 v[0:1], off
	v_lshl_add_u64 v[6:7], v[0:1], 0, s[18:19]
	s_mov_b32 m0, s5
	s_mov_b64 s[38:39], 0x20000
	v_readfirstlane_b32 s5, v123
	v_add_u32_e32 v124, 0x3000, v121
	global_load_lds_dwordx4 v[6:7], off
	v_lshl_add_u64 v[6:7], v[0:1], 0, s[38:39]
	s_mov_b32 m0, s5
	s_mov_b64 s[52:53], 0x30000
	v_readfirstlane_b32 s5, v124
	v_add_u32_e32 v125, 0x4000, v121
	global_load_lds_dwordx4 v[6:7], off
	v_lshl_add_u64 v[6:7], v[0:1], 0, s[52:53]
	s_mov_b32 m0, s5
	s_mov_b64 s[72:73], 0x40000
	v_readfirstlane_b32 s5, v125
	v_add_u32_e32 v126, 0x5000, v121
	global_load_lds_dwordx4 v[6:7], off
	v_lshl_add_u64 v[6:7], v[0:1], 0, s[72:73]
	s_mov_b32 m0, s5
	s_mov_b64 s[72:73], 0x50000
	v_readfirstlane_b32 s5, v126
	v_add_u32_e32 v127, 0xc000, v121
	global_load_lds_dwordx4 v[6:7], off
	v_lshl_add_u64 v[0:1], v[0:1], 0, s[72:73]
	s_mov_b32 m0, s5
	v_readfirstlane_b32 s5, v127
	v_add_u32_e32 v128, 0xd000, v121
	global_load_lds_dwordx4 v[0:1], off
	v_lshl_add_u64 v[0:1], v[4:5], 0, v[98:99]
	s_mov_b32 m0, s5
	v_readfirstlane_b32 s5, v128
	v_add_u32_e32 v129, 0xe000, v121
	global_load_lds_dwordx4 v[0:1], off
	v_lshl_add_u64 v[4:5], v[0:1], 0, s[18:19]
	s_mov_b32 m0, s5
	v_readfirstlane_b32 s5, v129
	v_add_u32_e32 v130, 0xf000, v121
	global_load_lds_dwordx4 v[4:5], off
	v_lshl_add_u64 v[4:5], v[0:1], 0, s[38:39]
	s_mov_b32 m0, s5
	v_readfirstlane_b32 s5, v130
	global_load_lds_dwordx4 v[4:5], off
	v_lshl_add_u64 v[0:1], v[0:1], 0, s[52:53]
	s_mov_b32 m0, s5
	s_add_i32 s1, s1, s15
	global_load_lds_dwordx4 v[0:1], off
	s_mul_i32 s4, s20, s4
	s_sub_i32 s1, s1, s4
	s_sub_i32 s1, s1, s16
	s_sub_i32 s0, s1, s0
	v_readlane_b32 s1, v218, 33
	v_lshlrev_b32_e32 v0, 7, v97
	s_mul_i32 s0, s1, s0
	v_and_b32_e32 v0, 0x2f80, v0
	s_add_i32 s0, s0, s46
	v_add_u32_e32 v153, 0, v0
	v_add_u32_e32 v155, s10, v0
	v_add_u32_e32 v0, s0, v8
	v_ashrrev_i32_e32 v1, 31, v0
	v_and_b32_e32 v108, 31, v97
	s_waitcnt vmcnt(0)
	v_lshlrev_b64 v[0:1], 11, v[0:1]
	v_or_b32_e32 v9, v115, v108
	v_lshlrev_b32_e32 v154, 4, v10
	v_lshl_add_u64 v[102:103], s[70:71], 0, v[0:1]
	v_mov_b32_e32 v0, 0
	v_lshl_add_u32 v131, v9, 7, 0
	v_xor_b32_e32 v156, 32, v154
	v_xor_b32_e32 v157, 64, v154
	v_xor_b32_e32 v158, 0x60, v154
	v_lshl_add_u64 v[100:101], s[70:71], 0, v[2:3]
	s_mov_b32 s4, 0
	v_mov_b32_e32 v1, v0
	v_mov_b32_e32 v2, v0
	v_mov_b32_e32 v3, v0
	v_mov_b32_e32 v4, v0
	v_mov_b32_e32 v5, v0
	v_mov_b32_e32 v6, v0
	v_mov_b32_e32 v7, v0
	v_mov_b32_e32 v8, v0
	v_mov_b32_e32 v9, v0
	v_mov_b32_e32 v10, v0
	v_mov_b32_e32 v11, v0
	v_mov_b32_e32 v12, v0
	v_mov_b32_e32 v13, v0
	v_mov_b32_e32 v14, v0
	v_mov_b32_e32 v15, v0
	v_mov_b32_e32 v16, v0
	v_mov_b32_e32 v17, v0
	v_mov_b32_e32 v18, v0
	v_mov_b32_e32 v19, v0
	v_mov_b32_e32 v20, v0
	v_mov_b32_e32 v21, v0
	v_mov_b32_e32 v22, v0
	v_mov_b32_e32 v23, v0
	v_mov_b32_e32 v24, v0
	v_mov_b32_e32 v25, v0
	v_mov_b32_e32 v26, v0
	v_mov_b32_e32 v27, v0
	v_mov_b32_e32 v28, v0
	v_mov_b32_e32 v29, v0
	v_mov_b32_e32 v30, v0
	v_mov_b32_e32 v31, v0
	v_mov_b32_e32 v32, v0
	v_mov_b32_e32 v33, v0
	v_mov_b32_e32 v34, v0
	v_mov_b32_e32 v35, v0
	v_mov_b32_e32 v36, v0
	v_mov_b32_e32 v37, v0
	v_mov_b32_e32 v38, v0
	v_mov_b32_e32 v39, v0
	v_mov_b32_e32 v40, v0
	v_mov_b32_e32 v41, v0
	v_mov_b32_e32 v42, v0
	v_mov_b32_e32 v43, v0
	v_mov_b32_e32 v44, v0
	v_mov_b32_e32 v45, v0
	v_mov_b32_e32 v46, v0
	v_mov_b32_e32 v47, v0
	v_mov_b32_e32 v48, v0
	s_waitcnt vmcnt(0)
; template <int EPI, int MI>
; DI void gemm_tile(const GemmDesc& g, int tm, int tn, char* smem) {
;     ...
;   const int rowA = wm * (32 * MI) + r, rowB = wn * 64 + r;
;   const int hk = hh ^ ((r & 7) ^ ((r >> 3) & 3));
;     ...
;   G_GLDS(0, 0);
;   asm volatile("s_waitcnt vmcnt(0)" ::: "memory");
;   __syncthreads();
;   for (int kt = 0; kt < nk; kt += 2) {
;     if (kt + 1 < nk) G_GLDS(kt + 1, 1);
;     G_COMPUTE(0);
;     asm volatile("s_waitcnt vmcnt(0)" ::: "memory");
;     __syncthreads();
;     if (kt + 1 < nk) {
;       if (kt + 2 < nk) G_GLDS(kt + 2, 0);
;       G_COMPUTE(1);
;       asm volatile("s_waitcnt vmcnt(0)" ::: "memory");
;       __syncthreads();
;     }
;   }
	v_mov_b32_e32 v49, v0
	v_mov_b32_e32 v50, v0
	v_mov_b32_e32 v51, v0
	v_mov_b32_e32 v52, v0
	v_mov_b32_e32 v53, v0
	v_mov_b32_e32 v54, v0
	v_mov_b32_e32 v55, v0
	v_mov_b32_e32 v56, v0
	v_mov_b32_e32 v57, v0
	v_mov_b32_e32 v58, v0
	v_mov_b32_e32 v59, v0
	v_mov_b32_e32 v60, v0
	v_mov_b32_e32 v61, v0
	v_mov_b32_e32 v62, v0
	v_mov_b32_e32 v63, v0
	v_mov_b32_e32 v64, v0
	v_mov_b32_e32 v65, v0
	v_mov_b32_e32 v66, v0
	v_mov_b32_e32 v67, v0
	v_mov_b32_e32 v68, v0
	v_mov_b32_e32 v69, v0
	v_mov_b32_e32 v70, v0
	v_mov_b32_e32 v71, v0
	v_mov_b32_e32 v72, v0
	v_mov_b32_e32 v73, v0
	v_mov_b32_e32 v74, v0
	v_mov_b32_e32 v75, v0
	v_mov_b32_e32 v76, v0
	v_mov_b32_e32 v77, v0
	v_mov_b32_e32 v78, v0
	v_mov_b32_e32 v79, v0
	v_mov_b32_e32 v80, v0
	v_mov_b32_e32 v81, v0
	v_mov_b32_e32 v82, v0
	v_mov_b32_e32 v83, v0
	v_mov_b32_e32 v84, v0
	v_mov_b32_e32 v85, v0
	v_mov_b32_e32 v86, v0
	v_mov_b32_e32 v87, v0
	v_mov_b32_e32 v88, v0
	v_mov_b32_e32 v89, v0
	v_mov_b32_e32 v90, v0
	v_mov_b32_e32 v91, v0
	v_mov_b32_e32 v92, v0
	v_mov_b32_e32 v93, v0
	v_mov_b32_e32 v94, v0
	v_mov_b32_e32 v95, v0
	v_add_u32_e32 v162, v131, v154
	v_add_u32_e32 v163, v131, v156
	v_add_u32_e32 v164, v131, v157
	v_add_u32_e32 v165, v131, v158
	v_add_u32_e32 v166, v153, v154
	v_add_u32_e32 v167, v153, v156
	v_add_u32_e32 v168, v153, v157
	v_add_u32_e32 v169, v153, v158
	v_add_u32_e32 v170, v155, v154
	v_add_u32_e32 v171, v155, v156
	v_add_u32_e32 v172, v155, v157
	v_add_u32_e32 v173, v155, v158
	v_lshl_add_u64 v[252:253], v[102:103], 0, v[98:99]
	v_lshl_add_u64 v[254:255], v[100:101], 0, v[98:99]
	v_readfirstlane_b32 s100, v121
	s_mov_b64 s[0:1], 0x80
	s_waitcnt vmcnt(0) lgkmcnt(0)
	s_barrier
	ds_read_b128 v[236:239], v166 offset:49152
	ds_read_b128 v[240:243], v166 offset:53248
	ds_read_b128 v[224:227], v162
	ds_read_b128 v[228:231], v162 offset:4096
	s_mov_b32 s101, 0
.Lgw_loop:
	ds_read_b128 v[232:235], v162 offset:8192
	s_waitcnt lgkmcnt(2)
	v_mfma_f32_32x32x16_bf16 v[80:95], v[224:227], v[236:239], v[80:95]
	v_mfma_f32_32x32x16_bf16 v[64:79], v[224:227], v[240:243], v[64:79]
	s_add_u32 m0, s100, 0x6000
	v_lshl_add_u64 v[106:107], v[252:253], 0, s[96:97]
	global_load_lds_dwordx4 v[106:107], off
	ds_read_b128 v[244:247], v167 offset:49152
	ds_read_b128 v[248:251], v167 offset:53248
	ds_read_b128 v[224:227], v163
	s_waitcnt lgkmcnt(4)
	v_mfma_f32_32x32x16_bf16 v[48:63], v[228:231], v[236:239], v[48:63]
	v_mfma_f32_32x32x16_bf16 v[32:47], v[228:231], v[240:243], v[32:47]
	s_add_u32 m0, s100, 0x7000
	v_lshl_add_u64 v[106:107], v[252:253], 0, s[50:51]
	global_load_lds_dwordx4 v[106:107], off
	ds_read_b128 v[228:231], v163 offset:4096
	s_waitcnt lgkmcnt(4)
	v_mfma_f32_32x32x16_bf16 v[16:31], v[232:235], v[236:239], v[16:31]
	v_mfma_f32_32x32x16_bf16 v[0:15], v[232:235], v[240:243], v[0:15]
	s_add_u32 m0, s100, 0x8000
	v_lshl_add_u64 v[106:107], v[252:253], 0, s[24:25]
	global_load_lds_dwordx4 v[106:107], off
	ds_read_b128 v[232:235], v163 offset:8192
	s_waitcnt lgkmcnt(2)
	v_mfma_f32_32x32x16_bf16 v[80:95], v[224:227], v[244:247], v[80:95]
	v_mfma_f32_32x32x16_bf16 v[64:79], v[224:227], v[248:251], v[64:79]
	s_add_u32 m0, s100, 0x9000
	v_lshl_add_u64 v[106:107], v[252:253], 0, s[26:27]
	global_load_lds_dwordx4 v[106:107], off
	ds_read_b128 v[236:239], v168 offset:49152
	ds_read_b128 v[240:243], v168 offset:53248
	ds_read_b128 v[224:227], v164
	s_waitcnt lgkmcnt(4)
	v_mfma_f32_32x32x16_bf16 v[48:63], v[228:231], v[244:247], v[48:63]
	v_mfma_f32_32x32x16_bf16 v[32:47], v[228:231], v[248:251], v[32:47]
	s_add_u32 m0, s100, 0xa000
	v_lshl_add_u64 v[106:107], v[252:253], 0, s[28:29]
	global_load_lds_dwordx4 v[106:107], off
	ds_read_b128 v[228:231], v164 offset:4096
	s_waitcnt lgkmcnt(4)
	v_mfma_f32_32x32x16_bf16 v[16:31], v[232:235], v[244:247], v[16:31]
	v_mfma_f32_32x32x16_bf16 v[0:15], v[232:235], v[248:251], v[0:15]
	s_add_u32 m0, s100, 0xb000
	v_lshl_add_u64 v[106:107], v[252:253], 0, s[30:31]
	global_load_lds_dwordx4 v[106:107], off
	v_lshl_add_u64 v[252:253], v[252:253], 0, s[0:1]
	ds_read_b128 v[232:235], v164 offset:8192
	s_waitcnt lgkmcnt(2)
	v_mfma_f32_32x32x16_bf16 v[80:95], v[224:227], v[236:239], v[80:95]
	v_mfma_f32_32x32x16_bf16 v[64:79], v[224:227], v[240:243], v[64:79]
	s_mov_b64 s[16:17], 0x2100080
	s_add_u32 m0, s100, 0x10000
	v_lshl_add_u64 v[106:107], v[254:255], 0, s[16:17]
	global_load_lds_dwordx4 v[106:107], off
	ds_read_b128 v[244:247], v169 offset:49152
	ds_read_b128 v[248:251], v169 offset:53248
	ds_read_b128 v[224:227], v165
	s_waitcnt lgkmcnt(4)
	v_mfma_f32_32x32x16_bf16 v[48:63], v[228:231], v[236:239], v[48:63]
	v_mfma_f32_32x32x16_bf16 v[32:47], v[228:231], v[240:243], v[32:47]
	s_mov_b64 s[16:17], 0x2110080
	s_add_u32 m0, s100, 0x11000
	v_lshl_add_u64 v[106:107], v[254:255], 0, s[16:17]
	global_load_lds_dwordx4 v[106:107], off
	ds_read_b128 v[228:231], v165 offset:4096
	s_waitcnt lgkmcnt(4)
	v_mfma_f32_32x32x16_bf16 v[16:31], v[232:235], v[236:239], v[16:31]
	v_mfma_f32_32x32x16_bf16 v[0:15], v[232:235], v[240:243], v[0:15]
	s_mov_b64 s[16:17], 0x2120080
	s_add_u32 m0, s100, 0x12000
	v_lshl_add_u64 v[106:107], v[254:255], 0, s[16:17]
	global_load_lds_dwordx4 v[106:107], off
	ds_read_b128 v[232:235], v165 offset:8192
	s_waitcnt lgkmcnt(2)
	v_mfma_f32_32x32x16_bf16 v[80:95], v[224:227], v[244:247], v[80:95]
	v_mfma_f32_32x32x16_bf16 v[64:79], v[224:227], v[248:251], v[64:79]
	s_mov_b64 s[16:17], 0x2130080
	s_add_u32 m0, s100, 0x13000
	v_lshl_add_u64 v[106:107], v[254:255], 0, s[16:17]
	global_load_lds_dwordx4 v[106:107], off
	v_lshl_add_u64 v[254:255], v[254:255], 0, s[0:1]
	s_waitcnt lgkmcnt(0)
	s_waitcnt vmcnt(0)
	s_barrier
; template <int EPI, int MI>
; DI void gemm_tile(const GemmDesc& g, int tm, int tn, char* smem) {
;     ...
;   G_GLDS(0, 0);
;   asm volatile("s_waitcnt vmcnt(0)" ::: "memory");
;   __syncthreads();
;   for (int kt = 0; kt < nk; kt += 2) {
;     if (kt + 1 < nk) G_GLDS(kt + 1, 1);
;     G_COMPUTE(0);
;     asm volatile("s_waitcnt vmcnt(0)" ::: "memory");
;     __syncthreads();
;     if (kt + 1 < nk) {
;       if (kt + 2 < nk) G_GLDS(kt + 2, 0);
;       G_COMPUTE(1);
;       asm volatile("s_waitcnt vmcnt(0)" ::: "memory");
;       __syncthreads();
;     }
;   }
	ds_read_b128 v[236:239], v170
	ds_read_b128 v[240:243], v170 offset:4096
	ds_read_b128 v[224:227], v162 offset:24576
	v_mfma_f32_32x32x16_bf16 v[48:63], v[228:231], v[244:247], v[48:63]
	v_mfma_f32_32x32x16_bf16 v[32:47], v[228:231], v[248:251], v[32:47]
	ds_read_b128 v[228:231], v162 offset:28672
	v_mfma_f32_32x32x16_bf16 v[16:31], v[232:235], v[244:247], v[16:31]
	v_mfma_f32_32x32x16_bf16 v[0:15], v[232:235], v[248:251], v[0:15]
	s_cmp_eq_u32 s101, 14
	s_cbranch_scc1 .Lgw_last
	ds_read_b128 v[232:235], v162 offset:32768
	s_waitcnt lgkmcnt(2)
	v_mfma_f32_32x32x16_bf16 v[80:95], v[224:227], v[236:239], v[80:95]
	v_mfma_f32_32x32x16_bf16 v[64:79], v[224:227], v[240:243], v[64:79]
	s_mov_b32 m0, s100
	v_lshl_add_u64 v[106:107], v[252:253], 0, s[96:97]
	global_load_lds_dwordx4 v[106:107], off
	ds_read_b128 v[244:247], v171
	ds_read_b128 v[248:251], v171 offset:4096
	ds_read_b128 v[224:227], v163 offset:24576
	s_waitcnt lgkmcnt(4)
	v_mfma_f32_32x32x16_bf16 v[48:63], v[228:231], v[236:239], v[48:63]
	v_mfma_f32_32x32x16_bf16 v[32:47], v[228:231], v[240:243], v[32:47]
	s_add_u32 m0, s100, 0x1000
	v_lshl_add_u64 v[106:107], v[252:253], 0, s[50:51]
	global_load_lds_dwordx4 v[106:107], off
	ds_read_b128 v[228:231], v163 offset:28672
	s_waitcnt lgkmcnt(4)
	v_mfma_f32_32x32x16_bf16 v[16:31], v[232:235], v[236:239], v[16:31]
	v_mfma_f32_32x32x16_bf16 v[0:15], v[232:235], v[240:243], v[0:15]
	s_add_u32 m0, s100, 0x2000
	v_lshl_add_u64 v[106:107], v[252:253], 0, s[24:25]
	global_load_lds_dwordx4 v[106:107], off
	ds_read_b128 v[232:235], v163 offset:32768
	s_waitcnt lgkmcnt(2)
	v_mfma_f32_32x32x16_bf16 v[80:95], v[224:227], v[244:247], v[80:95]
	v_mfma_f32_32x32x16_bf16 v[64:79], v[224:227], v[248:251], v[64:79]
	s_add_u32 m0, s100, 0x3000
	v_lshl_add_u64 v[106:107], v[252:253], 0, s[26:27]
	global_load_lds_dwordx4 v[106:107], off
	ds_read_b128 v[236:239], v172
	ds_read_b128 v[240:243], v172 offset:4096
	ds_read_b128 v[224:227], v164 offset:24576
	s_waitcnt lgkmcnt(4)
	v_mfma_f32_32x32x16_bf16 v[48:63], v[228:231], v[244:247], v[48:63]
	v_mfma_f32_32x32x16_bf16 v[32:47], v[228:231], v[248:251], v[32:47]
	s_add_u32 m0, s100, 0x4000
	v_lshl_add_u64 v[106:107], v[252:253], 0, s[28:29]
	global_load_lds_dwordx4 v[106:107], off
	ds_read_b128 v[228:231], v164 offset:28672
	s_waitcnt lgkmcnt(4)
	v_mfma_f32_32x32x16_bf16 v[16:31], v[232:235], v[244:247], v[16:31]
	v_mfma_f32_32x32x16_bf16 v[0:15], v[232:235], v[248:251], v[0:15]
	s_add_u32 m0, s100, 0x5000
	v_lshl_add_u64 v[106:107], v[252:253], 0, s[30:31]
	global_load_lds_dwordx4 v[106:107], off
	v_lshl_add_u64 v[252:253], v[252:253], 0, s[0:1]
	ds_read_b128 v[232:235], v164 offset:32768
	s_waitcnt lgkmcnt(2)
	v_mfma_f32_32x32x16_bf16 v[80:95], v[224:227], v[236:239], v[80:95]
	v_mfma_f32_32x32x16_bf16 v[64:79], v[224:227], v[240:243], v[64:79]
	s_mov_b64 s[16:17], 0x2100080
	s_add_u32 m0, s100, 0xc000
	v_lshl_add_u64 v[106:107], v[254:255], 0, s[16:17]
	global_load_lds_dwordx4 v[106:107], off
	ds_read_b128 v[244:247], v173
	ds_read_b128 v[248:251], v173 offset:4096
	ds_read_b128 v[224:227], v165 offset:24576
	s_waitcnt lgkmcnt(4)
	v_mfma_f32_32x32x16_bf16 v[48:63], v[228:231], v[236:239], v[48:63]
	v_mfma_f32_32x32x16_bf16 v[32:47], v[228:231], v[240:243], v[32:47]
	s_mov_b64 s[16:17], 0x2110080
	s_add_u32 m0, s100, 0xd000
	v_lshl_add_u64 v[106:107], v[254:255], 0, s[16:17]
	global_load_lds_dwordx4 v[106:107], off
	ds_read_b128 v[228:231], v165 offset:28672
	s_waitcnt lgkmcnt(4)
	v_mfma_f32_32x32x16_bf16 v[16:31], v[232:235], v[236:239], v[16:31]
	v_mfma_f32_32x32x16_bf16 v[0:15], v[232:235], v[240:243], v[0:15]
	s_mov_b64 s[16:17], 0x2120080
	s_add_u32 m0, s100, 0xe000
	v_lshl_add_u64 v[106:107], v[254:255], 0, s[16:17]
	global_load_lds_dwordx4 v[106:107], off
	ds_read_b128 v[232:235], v165 offset:32768
	s_waitcnt lgkmcnt(2)
	v_mfma_f32_32x32x16_bf16 v[80:95], v[224:227], v[244:247], v[80:95]
	v_mfma_f32_32x32x16_bf16 v[64:79], v[224:227], v[248:251], v[64:79]
	s_mov_b64 s[16:17], 0x2130080
	s_add_u32 m0, s100, 0xf000
	v_lshl_add_u64 v[106:107], v[254:255], 0, s[16:17]
	global_load_lds_dwordx4 v[106:107], off
	v_lshl_add_u64 v[254:255], v[254:255], 0, s[0:1]
	s_waitcnt lgkmcnt(0)
	s_waitcnt vmcnt(0)
	s_barrier
	ds_read_b128 v[236:239], v166 offset:49152
	ds_read_b128 v[240:243], v166 offset:53248
	ds_read_b128 v[224:227], v162
	v_mfma_f32_32x32x16_bf16 v[48:63], v[228:231], v[244:247], v[48:63]
	v_mfma_f32_32x32x16_bf16 v[32:47], v[228:231], v[248:251], v[32:47]
	ds_read_b128 v[228:231], v162 offset:4096
	v_mfma_f32_32x32x16_bf16 v[16:31], v[232:235], v[244:247], v[16:31]
	v_mfma_f32_32x32x16_bf16 v[0:15], v[232:235], v[248:251], v[0:15]
	s_add_u32 s101, s101, 2
	s_branch .Lgw_loop

; template <int EPI, int MI>
; DI void gemm_tile(const GemmDesc& g, int tm, int tn, char* smem) {
;     ...
;   const int tid = get_tid(), lane = tid & 63, wave = tid >> 6, r = lane & 31, hh = lane >> 5;
;   const int wm = wave >> 1, wn = wave & 1;
;   const int m0 = tm * BM, n0 = tn * 128;
;   const int nk = g.K >> 6;
;   f32x16 acc[MI][2];
; #pragma unroll
;   for (int a = 0; a < MI; ++a)
; #pragma unroll
;     for (int b = 0; b < 2; ++b)
; #pragma unroll
;       for (int i = 0; i < 16; ++i) acc[a][b][i] = 0.f;
;   const int srow = tid >> 3;
;   const int schunk = (tid & 7) ^ ((srow & 7) ^ ((srow >> 3) & 3));
;     ...
;   const int rowA = wm * (32 * MI) + r, rowB = wn * 64 + r;
;   const int hk = hh ^ ((r & 7) ^ ((r >> 3) & 3));
;     ...
;   G_GLDS(0, 0);
;   asm volatile("s_waitcnt vmcnt(0)" ::: "memory");
;   __syncthreads();
; template <int EPI, int MI>
; DI void gemm_phase(const GemmDesc& g, char* smem, int vb, int nvb) {
;     ...
;   for (int q = start; q < local; q += step) {
;     const int mg = q / per;
;     const int rem = q - mg * per;
;     const int tn = rem / PM;
;     const int tm = mbase + mg * PM + (rem - tn * PM);
.LBB0_1421:
	s_abs_i32 s1, s5
	v_readlane_b32 s15, v219, 45
	s_mul_hi_u32 s15, s1, s15
	v_readlane_b32 s18, v219, 44
	s_mul_i32 s16, s15, s18
	s_sub_i32 s1, s1, s16
	s_ashr_i32 s0, s5, 31
	s_add_i32 s16, s15, 1
	s_sub_i32 s17, s1, s18
	s_cmp_ge_u32 s1, s18
	s_cselect_b32 s15, s16, s15
	s_cselect_b32 s1, s17, s1
	s_add_i32 s16, s15, 1
	s_cmp_ge_u32 s1, s18
	s_cselect_b32 s1, s16, s15
	s_xor_b32 s1, s1, s0
	s_sub_i32 s15, s1, s0
	s_mul_i32 s16, s15, s18
	s_sub_i32 s16, s5, s16
	s_abs_i32 s18, s16
	v_readlane_b32 s19, v219, 46
	s_mul_hi_u32 s19, s18, s19
	v_readlane_b32 s40, v218, 32
	s_mul_i32 s38, s19, s40
	s_sub_i32 s18, s18, s38
	s_ashr_i32 s17, s16, 31
	s_add_i32 s38, s19, 1
	s_sub_i32 s39, s18, s40
	s_cmp_ge_u32 s18, s40
	s_cselect_b32 s19, s38, s19
	s_cselect_b32 s18, s39, s18
	s_add_i32 s38, s19, 1
	s_cmp_ge_u32 s18, s40
	s_cselect_b32 s18, s38, s19
	s_xor_b32 s18, s18, s17
	s_sub_i32 s39, s18, s17
	s_sub_i32 s15, s15, s39
	v_mov_b32_e32 v6, v132
	s_mul_i32 s15, s15, s40
	s_add_i32 s16, s16, s54
	s_add_i32 s38, s16, s15
	v_ashrrev_i32_e32 v97, 3, v6
	v_ashrrev_i32_e32 v120, 7, v6
	v_bfe_u32 v0, v6, 6, 2
	v_xor_b32_e32 v1, v97, v6
	s_mulk_i32 s38, 0xc0
	v_and_b32_e32 v121, 31, v6
	v_bitop3_b32 v2, v1, v0, 7 bitop3:0x6c
	v_mul_lo_u32 v0, v120, s6
	v_and_b32_e32 v115, 7, v6
	v_or_b32_e32 v8, v0, v121
	v_lshrrev_b32_e32 v0, 3, v6
	s_waitcnt vmcnt(10)
	v_add_u32_e32 v98, s38, v97
	v_bfe_u32 v122, v6, 5, 1
	v_bitop3_b32 v0, v0, v115, 3 bitop3:0x6c
	v_ashrrev_i32_e32 v99, 31, v98
	v_readlane_b32 s40, v223, 59
	v_xor_b32_e32 v9, v0, v122
	v_lshlrev_b64 v[0:1], 11, v[98:99]
	v_readlane_b32 s41, v223, 60
	v_lshlrev_b32_e32 v100, 4, v2
	v_lshl_add_u32 v2, s39, 7, v97
	v_lshlrev_b32_e32 v99, 4, v6
	v_lshl_add_u64 v[0:1], s[40:41], 0, v[0:1]
	v_ashrrev_i32_e32 v3, 31, v2
	v_readlane_b32 s40, v220, 54
	v_add_u32_e32 v124, 0, v99
	v_mov_b32_e32 v101, v96
	v_lshlrev_b64 v[2:3], 11, v[2:3]
	v_readlane_b32 s41, v220, 55
	v_readfirstlane_b32 s15, v124
	v_add_u32_e32 v125, 0x1000, v124
	v_lshl_add_u64 v[0:1], v[0:1], 0, v[100:101]
	v_lshl_add_u64 v[4:5], s[40:41], 0, v[2:3]
	s_mov_b32 m0, s15
	s_mov_b64 s[40:41], 0x10000
	v_readfirstlane_b32 s15, v125
	v_add_u32_e32 v126, 0x2000, v124
	v_bfe_u32 v123, v6, 6, 1
	global_load_lds_dwordx4 v[0:1], off
	v_lshl_add_u64 v[6:7], v[0:1], 0, s[40:41]
	s_mov_b32 m0, s15
	s_mov_b64 s[42:43], 0x20000
	v_readfirstlane_b32 s15, v126
	v_add_u32_e32 v127, 0x3000, v124
	global_load_lds_dwordx4 v[6:7], off
	v_lshl_add_u64 v[6:7], v[0:1], 0, s[42:43]
	s_mov_b32 m0, s15
	s_mov_b64 s[44:45], 0x30000
	v_readfirstlane_b32 s15, v127
	v_add_u32_e32 v128, 0x4000, v124
	global_load_lds_dwordx4 v[6:7], off
	v_lshl_add_u64 v[6:7], v[0:1], 0, s[44:45]
	s_mov_b32 m0, s15
	s_mov_b64 s[46:47], 0x40000
	v_readfirstlane_b32 s15, v128
	v_add_u32_e32 v129, 0x5000, v124
	global_load_lds_dwordx4 v[6:7], off
	v_lshl_add_u64 v[6:7], v[0:1], 0, s[46:47]
	s_mov_b32 m0, s15
	s_mov_b64 s[46:47], 0x50000
	v_readfirstlane_b32 s15, v129
	v_add_u32_e32 v130, 0xc000, v124
	global_load_lds_dwordx4 v[6:7], off
	v_lshl_add_u64 v[0:1], v[0:1], 0, s[46:47]
	s_mov_b32 m0, s15
	v_readfirstlane_b32 s15, v130
	v_add_u32_e32 v131, 0xd000, v124
	global_load_lds_dwordx4 v[0:1], off
	v_lshl_add_u64 v[0:1], v[4:5], 0, v[100:101]
	s_mov_b32 m0, s15
	v_readfirstlane_b32 s15, v131
	v_add_u32_e32 v153, 0xe000, v124
	global_load_lds_dwordx4 v[0:1], off
	v_lshl_add_u64 v[4:5], v[0:1], 0, s[40:41]
	s_mov_b32 m0, s15
	v_readfirstlane_b32 s15, v153
	v_add_u32_e32 v154, 0xf000, v124
	global_load_lds_dwordx4 v[4:5], off
	v_lshl_add_u64 v[4:5], v[0:1], 0, s[42:43]
	s_mov_b32 m0, s15
	v_readfirstlane_b32 s15, v154
	global_load_lds_dwordx4 v[4:5], off
	v_lshl_add_u64 v[0:1], v[0:1], 0, s[44:45]
	s_mov_b32 m0, s15
	s_mul_i32 s0, s0, 43
	global_load_lds_dwordx4 v[0:1], off
	s_add_i32 s17, s17, s0
	s_sub_i32 s0, s17, s18
	s_mul_i32 s1, s1, 43
	s_sub_i32 s0, s0, s1
	v_readlane_b32 s1, v218, 33
	v_lshlrev_b32_e32 v0, 7, v121
	s_mul_i32 s0, s1, s0
	v_lshl_or_b32 v0, v123, 13, v0
	s_add_i32 s0, s0, s4
	v_add_u32_e32 v156, 0, v0
	v_add_u32_e32 v158, s10, v0
	v_add_u32_e32 v0, s0, v97
	v_ashrrev_i32_e32 v1, 31, v0
	s_waitcnt vmcnt(0)
	v_lshlrev_b64 v[0:1], 11, v[0:1]
	v_lshlrev_b32_e32 v157, 4, v9
	s_waitcnt vmcnt(0)
; template <int EPI, int MI>
; DI void gemm_tile(const GemmDesc& g, int tm, int tn, char* smem) {
;     ...
;   const int rowA = wm * (32 * MI) + r, rowB = wn * 64 + r;
;   const int hk = hh ^ ((r & 7) ^ ((r >> 3) & 3));
;     ...
;   G_GLDS(0, 0);
;   asm volatile("s_waitcnt vmcnt(0)" ::: "memory");
;   __syncthreads();
;   for (int kt = 0; kt < nk; kt += 2) {
;     if (kt + 1 < nk) G_GLDS(kt + 1, 1);
;     G_COMPUTE(0);
;     asm volatile("s_waitcnt vmcnt(0)" ::: "memory");
;     __syncthreads();
;     if (kt + 1 < nk) {
;       if (kt + 2 < nk) G_GLDS(kt + 2, 0);
;       G_COMPUTE(1);
;       asm volatile("s_waitcnt vmcnt(0)" ::: "memory");
;       __syncthreads();
;     }
;   }
	v_lshl_add_u64 v[102:103], s[70:71], 0, v[0:1]
	v_mov_b32_e32 v0, 0
	v_lshl_add_u32 v155, v8, 7, 0
	v_xor_b32_e32 v159, 32, v157
	v_xor_b32_e32 v160, 64, v157
	v_xor_b32_e32 v161, 0x60, v157
	v_lshl_add_u64 v[104:105], s[70:71], 0, v[2:3]
	s_mov_b32 s15, 0
	v_mov_b32_e32 v1, v0
	v_mov_b32_e32 v2, v0
	v_mov_b32_e32 v3, v0
	v_mov_b32_e32 v4, v0
	v_mov_b32_e32 v5, v0
	v_mov_b32_e32 v6, v0
	v_mov_b32_e32 v7, v0
	v_mov_b32_e32 v8, v0
	v_mov_b32_e32 v9, v0
	v_mov_b32_e32 v10, v0
	v_mov_b32_e32 v11, v0
	v_mov_b32_e32 v12, v0
	v_mov_b32_e32 v13, v0
	v_mov_b32_e32 v14, v0
	v_mov_b32_e32 v15, v0
	v_mov_b32_e32 v16, v0
	v_mov_b32_e32 v17, v0
	v_mov_b32_e32 v18, v0
	v_mov_b32_e32 v19, v0
	v_mov_b32_e32 v20, v0
	v_mov_b32_e32 v21, v0
	v_mov_b32_e32 v22, v0
	v_mov_b32_e32 v23, v0
	v_mov_b32_e32 v24, v0
	v_mov_b32_e32 v25, v0
	v_mov_b32_e32 v26, v0
	v_mov_b32_e32 v27, v0
	v_mov_b32_e32 v28, v0
	v_mov_b32_e32 v29, v0
	v_mov_b32_e32 v30, v0
	v_mov_b32_e32 v31, v0
	v_mov_b32_e32 v32, v0
	v_mov_b32_e32 v33, v0
	v_mov_b32_e32 v34, v0
	v_mov_b32_e32 v35, v0
	v_mov_b32_e32 v36, v0
	v_mov_b32_e32 v37, v0
	v_mov_b32_e32 v38, v0
	v_mov_b32_e32 v39, v0
	v_mov_b32_e32 v40, v0
	v_mov_b32_e32 v41, v0
	v_mov_b32_e32 v42, v0
	v_mov_b32_e32 v43, v0
	v_mov_b32_e32 v44, v0
	v_mov_b32_e32 v45, v0
	v_mov_b32_e32 v46, v0
	v_mov_b32_e32 v47, v0
	v_mov_b32_e32 v48, v0
	v_mov_b32_e32 v49, v0
	v_mov_b32_e32 v50, v0
	v_mov_b32_e32 v51, v0
	v_mov_b32_e32 v52, v0
	v_mov_b32_e32 v53, v0
	v_mov_b32_e32 v54, v0
	v_mov_b32_e32 v55, v0
	v_mov_b32_e32 v56, v0
	v_mov_b32_e32 v57, v0
	v_mov_b32_e32 v58, v0
	v_mov_b32_e32 v59, v0
	v_mov_b32_e32 v60, v0
	v_mov_b32_e32 v61, v0
	v_mov_b32_e32 v62, v0
	v_mov_b32_e32 v63, v0
	v_mov_b32_e32 v64, v0
	v_mov_b32_e32 v65, v0
	v_mov_b32_e32 v66, v0
	v_mov_b32_e32 v67, v0
	v_mov_b32_e32 v68, v0
	v_mov_b32_e32 v69, v0
	v_mov_b32_e32 v70, v0
	v_mov_b32_e32 v71, v0
	v_mov_b32_e32 v72, v0
	v_mov_b32_e32 v73, v0
	v_mov_b32_e32 v74, v0
	v_mov_b32_e32 v75, v0
	v_mov_b32_e32 v76, v0
	v_mov_b32_e32 v77, v0
	v_mov_b32_e32 v78, v0
	v_mov_b32_e32 v79, v0
	v_mov_b32_e32 v80, v0
	v_mov_b32_e32 v81, v0
	v_mov_b32_e32 v82, v0
	v_mov_b32_e32 v83, v0
	v_mov_b32_e32 v84, v0
	v_mov_b32_e32 v85, v0
	v_mov_b32_e32 v86, v0
	v_mov_b32_e32 v87, v0
	v_mov_b32_e32 v88, v0
	v_mov_b32_e32 v89, v0
	v_mov_b32_e32 v90, v0
	v_mov_b32_e32 v91, v0
	v_mov_b32_e32 v92, v0
	v_mov_b32_e32 v93, v0
	v_mov_b32_e32 v94, v0
	v_mov_b32_e32 v95, v0
	v_add_u32_e32 v162, v155, v157
	v_add_u32_e32 v163, v155, v159
	v_add_u32_e32 v164, v155, v160
	v_add_u32_e32 v165, v155, v161
	v_add_u32_e32 v166, v156, v157
	v_add_u32_e32 v167, v156, v159
	v_add_u32_e32 v168, v156, v160
	v_add_u32_e32 v169, v156, v161
	v_add_u32_e32 v170, v158, v157
	v_add_u32_e32 v171, v158, v159
	v_add_u32_e32 v172, v158, v160
	v_add_u32_e32 v173, v158, v161
	v_lshl_add_u64 v[252:253], v[102:103], 0, v[100:101]
	v_lshl_add_u64 v[254:255], v[104:105], 0, v[100:101]
	v_readfirstlane_b32 s100, v124
	s_mov_b64 s[0:1], 0x80
	s_waitcnt vmcnt(0) lgkmcnt(0)
	s_barrier
	ds_read_b128 v[236:239], v166 offset:49152
	ds_read_b128 v[240:243], v166 offset:53248
	ds_read_b128 v[224:227], v162
	ds_read_b128 v[228:231], v162 offset:4096
	s_mov_b32 s101, 0
.Lgb_loop:
	ds_read_b128 v[232:235], v162 offset:8192
	s_waitcnt lgkmcnt(2)
	v_mfma_f32_32x32x16_bf16 v[80:95], v[224:227], v[236:239], v[80:95]
	v_mfma_f32_32x32x16_bf16 v[64:79], v[224:227], v[240:243], v[64:79]
	s_add_u32 m0, s100, 0x6000
	v_lshl_add_u64 v[106:107], v[252:253], 0, s[96:97]
	global_load_lds_dwordx4 v[106:107], off
	ds_read_b128 v[244:247], v167 offset:49152
	ds_read_b128 v[248:251], v167 offset:53248
	ds_read_b128 v[224:227], v163
	s_waitcnt lgkmcnt(4)
	v_mfma_f32_32x32x16_bf16 v[48:63], v[228:231], v[236:239], v[48:63]
	v_mfma_f32_32x32x16_bf16 v[32:47], v[228:231], v[240:243], v[32:47]
	s_add_u32 m0, s100, 0x7000
	v_lshl_add_u64 v[106:107], v[252:253], 0, s[50:51]
	global_load_lds_dwordx4 v[106:107], off
	ds_read_b128 v[228:231], v163 offset:4096
	s_waitcnt lgkmcnt(4)
	v_mfma_f32_32x32x16_bf16 v[16:31], v[232:235], v[236:239], v[16:31]
	v_mfma_f32_32x32x16_bf16 v[0:15], v[232:235], v[240:243], v[0:15]
	s_add_u32 m0, s100, 0x8000
	v_lshl_add_u64 v[106:107], v[252:253], 0, s[24:25]
	global_load_lds_dwordx4 v[106:107], off
	ds_read_b128 v[232:235], v163 offset:8192
	s_waitcnt lgkmcnt(2)
	v_mfma_f32_32x32x16_bf16 v[80:95], v[224:227], v[244:247], v[80:95]
	v_mfma_f32_32x32x16_bf16 v[64:79], v[224:227], v[248:251], v[64:79]
	s_add_u32 m0, s100, 0x9000
	v_lshl_add_u64 v[106:107], v[252:253], 0, s[26:27]
	global_load_lds_dwordx4 v[106:107], off
	ds_read_b128 v[236:239], v168 offset:49152
	ds_read_b128 v[240:243], v168 offset:53248
	ds_read_b128 v[224:227], v164
	s_waitcnt lgkmcnt(4)
	v_mfma_f32_32x32x16_bf16 v[48:63], v[228:231], v[244:247], v[48:63]
	v_mfma_f32_32x32x16_bf16 v[32:47], v[228:231], v[248:251], v[32:47]
	s_add_u32 m0, s100, 0xa000
	v_lshl_add_u64 v[106:107], v[252:253], 0, s[28:29]
	global_load_lds_dwordx4 v[106:107], off
	ds_read_b128 v[228:231], v164 offset:4096
	s_waitcnt lgkmcnt(4)
	v_mfma_f32_32x32x16_bf16 v[16:31], v[232:235], v[244:247], v[16:31]
	v_mfma_f32_32x32x16_bf16 v[0:15], v[232:235], v[248:251], v[0:15]
	s_add_u32 m0, s100, 0xb000
	v_lshl_add_u64 v[106:107], v[252:253], 0, s[30:31]
	global_load_lds_dwordx4 v[106:107], off
	v_lshl_add_u64 v[252:253], v[252:253], 0, s[0:1]
	ds_read_b128 v[232:235], v164 offset:8192
	s_waitcnt lgkmcnt(2)
	v_mfma_f32_32x32x16_bf16 v[80:95], v[224:227], v[236:239], v[80:95]
	v_mfma_f32_32x32x16_bf16 v[64:79], v[224:227], v[240:243], v[64:79]
	s_mov_b64 s[16:17], 0xb00080
	s_add_u32 m0, s100, 0x10000
	v_lshl_add_u64 v[106:107], v[254:255], 0, s[16:17]
	global_load_lds_dwordx4 v[106:107], off
	ds_read_b128 v[244:247], v169 offset:49152
	ds_read_b128 v[248:251], v169 offset:53248
	ds_read_b128 v[224:227], v165
	s_waitcnt lgkmcnt(4)
	v_mfma_f32_32x32x16_bf16 v[48:63], v[228:231], v[236:239], v[48:63]
	v_mfma_f32_32x32x16_bf16 v[32:47], v[228:231], v[240:243], v[32:47]
	s_mov_b64 s[16:17], 0xb10080
	s_add_u32 m0, s100, 0x11000
	v_lshl_add_u64 v[106:107], v[254:255], 0, s[16:17]
	global_load_lds_dwordx4 v[106:107], off
	ds_read_b128 v[228:231], v165 offset:4096
	s_waitcnt lgkmcnt(4)
	v_mfma_f32_32x32x16_bf16 v[16:31], v[232:235], v[236:239], v[16:31]
	v_mfma_f32_32x32x16_bf16 v[0:15], v[232:235], v[240:243], v[0:15]
	s_mov_b64 s[16:17], 0xb20080
	s_add_u32 m0, s100, 0x12000
	v_lshl_add_u64 v[106:107], v[254:255], 0, s[16:17]
	global_load_lds_dwordx4 v[106:107], off
	ds_read_b128 v[232:235], v165 offset:8192
	s_waitcnt lgkmcnt(2)
	v_mfma_f32_32x32x16_bf16 v[80:95], v[224:227], v[244:247], v[80:95]
	v_mfma_f32_32x32x16_bf16 v[64:79], v[224:227], v[248:251], v[64:79]
	s_mov_b64 s[16:17], 0xb30080
	s_add_u32 m0, s100, 0x13000
	v_lshl_add_u64 v[106:107], v[254:255], 0, s[16:17]
	global_load_lds_dwordx4 v[106:107], off
	v_lshl_add_u64 v[254:255], v[254:255], 0, s[0:1]
	s_waitcnt lgkmcnt(0)
	s_waitcnt vmcnt(0)
	s_barrier
; template <int EPI, int MI>
; DI void gemm_tile(const GemmDesc& g, int tm, int tn, char* smem) {
;     ...
;   G_GLDS(0, 0);
;   asm volatile("s_waitcnt vmcnt(0)" ::: "memory");
;   __syncthreads();
;   for (int kt = 0; kt < nk; kt += 2) {
;     if (kt + 1 < nk) G_GLDS(kt + 1, 1);
;     G_COMPUTE(0);
;     asm volatile("s_waitcnt vmcnt(0)" ::: "memory");
;     __syncthreads();
;     if (kt + 1 < nk) {
;       if (kt + 2 < nk) G_GLDS(kt + 2, 0);
;       G_COMPUTE(1);
;       asm volatile("s_waitcnt vmcnt(0)" ::: "memory");
;       __syncthreads();
;     }
;   }
	ds_read_b128 v[236:239], v170
	ds_read_b128 v[240:243], v170 offset:4096
	ds_read_b128 v[224:227], v162 offset:24576
	v_mfma_f32_32x32x16_bf16 v[48:63], v[228:231], v[244:247], v[48:63]
	v_mfma_f32_32x32x16_bf16 v[32:47], v[228:231], v[248:251], v[32:47]
	ds_read_b128 v[228:231], v162 offset:28672
	v_mfma_f32_32x32x16_bf16 v[16:31], v[232:235], v[244:247], v[16:31]
	v_mfma_f32_32x32x16_bf16 v[0:15], v[232:235], v[248:251], v[0:15]
	s_cmp_eq_u32 s101, 14
	s_cbranch_scc1 .Lgb_last
	ds_read_b128 v[232:235], v162 offset:32768
	s_waitcnt lgkmcnt(2)
	v_mfma_f32_32x32x16_bf16 v[80:95], v[224:227], v[236:239], v[80:95]
	v_mfma_f32_32x32x16_bf16 v[64:79], v[224:227], v[240:243], v[64:79]
	s_mov_b32 m0, s100
	v_lshl_add_u64 v[106:107], v[252:253], 0, s[96:97]
	global_load_lds_dwordx4 v[106:107], off
	ds_read_b128 v[244:247], v171
	ds_read_b128 v[248:251], v171 offset:4096
	ds_read_b128 v[224:227], v163 offset:24576
	s_waitcnt lgkmcnt(4)
	v_mfma_f32_32x32x16_bf16 v[48:63], v[228:231], v[236:239], v[48:63]
	v_mfma_f32_32x32x16_bf16 v[32:47], v[228:231], v[240:243], v[32:47]
	s_add_u32 m0, s100, 0x1000
	v_lshl_add_u64 v[106:107], v[252:253], 0, s[50:51]
	global_load_lds_dwordx4 v[106:107], off
	ds_read_b128 v[228:231], v163 offset:28672
	s_waitcnt lgkmcnt(4)
	v_mfma_f32_32x32x16_bf16 v[16:31], v[232:235], v[236:239], v[16:31]
	v_mfma_f32_32x32x16_bf16 v[0:15], v[232:235], v[240:243], v[0:15]
	s_add_u32 m0, s100, 0x2000
	v_lshl_add_u64 v[106:107], v[252:253], 0, s[24:25]
	global_load_lds_dwordx4 v[106:107], off
	ds_read_b128 v[232:235], v163 offset:32768
	s_waitcnt lgkmcnt(2)
	v_mfma_f32_32x32x16_bf16 v[80:95], v[224:227], v[244:247], v[80:95]
	v_mfma_f32_32x32x16_bf16 v[64:79], v[224:227], v[248:251], v[64:79]
	s_add_u32 m0, s100, 0x3000
	v_lshl_add_u64 v[106:107], v[252:253], 0, s[26:27]
	global_load_lds_dwordx4 v[106:107], off
	ds_read_b128 v[236:239], v172
	ds_read_b128 v[240:243], v172 offset:4096
	ds_read_b128 v[224:227], v164 offset:24576
	s_waitcnt lgkmcnt(4)
	v_mfma_f32_32x32x16_bf16 v[48:63], v[228:231], v[244:247], v[48:63]
	v_mfma_f32_32x32x16_bf16 v[32:47], v[228:231], v[248:251], v[32:47]
	s_add_u32 m0, s100, 0x4000
	v_lshl_add_u64 v[106:107], v[252:253], 0, s[28:29]
	global_load_lds_dwordx4 v[106:107], off
	ds_read_b128 v[228:231], v164 offset:28672
	s_waitcnt lgkmcnt(4)
	v_mfma_f32_32x32x16_bf16 v[16:31], v[232:235], v[244:247], v[16:31]
	v_mfma_f32_32x32x16_bf16 v[0:15], v[232:235], v[248:251], v[0:15]
	s_add_u32 m0, s100, 0x5000
	v_lshl_add_u64 v[106:107], v[252:253], 0, s[30:31]
	global_load_lds_dwordx4 v[106:107], off
	v_lshl_add_u64 v[252:253], v[252:253], 0, s[0:1]
	ds_read_b128 v[232:235], v164 offset:32768
	s_waitcnt lgkmcnt(2)
	v_mfma_f32_32x32x16_bf16 v[80:95], v[224:227], v[236:239], v[80:95]
	v_mfma_f32_32x32x16_bf16 v[64:79], v[224:227], v[240:243], v[64:79]
	s_mov_b64 s[16:17], 0xb00080
	s_add_u32 m0, s100, 0xc000
	v_lshl_add_u64 v[106:107], v[254:255], 0, s[16:17]
	global_load_lds_dwordx4 v[106:107], off
	ds_read_b128 v[244:247], v173
	ds_read_b128 v[248:251], v173 offset:4096
	ds_read_b128 v[224:227], v165 offset:24576
	s_waitcnt lgkmcnt(4)
	v_mfma_f32_32x32x16_bf16 v[48:63], v[228:231], v[236:239], v[48:63]
	v_mfma_f32_32x32x16_bf16 v[32:47], v[228:231], v[240:243], v[32:47]
	s_mov_b64 s[16:17], 0xb10080
	s_add_u32 m0, s100, 0xd000
	v_lshl_add_u64 v[106:107], v[254:255], 0, s[16:17]
	global_load_lds_dwordx4 v[106:107], off
	ds_read_b128 v[228:231], v165 offset:28672
	s_waitcnt lgkmcnt(4)
	v_mfma_f32_32x32x16_bf16 v[16:31], v[232:235], v[236:239], v[16:31]
	v_mfma_f32_32x32x16_bf16 v[0:15], v[232:235], v[240:243], v[0:15]
	s_mov_b64 s[16:17], 0xb20080
	s_add_u32 m0, s100, 0xe000
	v_lshl_add_u64 v[106:107], v[254:255], 0, s[16:17]
	global_load_lds_dwordx4 v[106:107], off
	ds_read_b128 v[232:235], v165 offset:32768
	s_waitcnt lgkmcnt(2)
	v_mfma_f32_32x32x16_bf16 v[80:95], v[224:227], v[244:247], v[80:95]
	v_mfma_f32_32x32x16_bf16 v[64:79], v[224:227], v[248:251], v[64:79]
	s_mov_b64 s[16:17], 0xb30080
	s_add_u32 m0, s100, 0xf000
	v_lshl_add_u64 v[106:107], v[254:255], 0, s[16:17]
	global_load_lds_dwordx4 v[106:107], off
	v_lshl_add_u64 v[254:255], v[254:255], 0, s[0:1]
	s_waitcnt lgkmcnt(0)
	s_waitcnt vmcnt(0)
	s_barrier
	ds_read_b128 v[236:239], v166 offset:49152
	ds_read_b128 v[240:243], v166 offset:53248
	ds_read_b128 v[224:227], v162
	v_mfma_f32_32x32x16_bf16 v[48:63], v[228:231], v[244:247], v[48:63]
	v_mfma_f32_32x32x16_bf16 v[32:47], v[228:231], v[248:251], v[32:47]
	ds_read_b128 v[228:231], v162 offset:4096
	v_mfma_f32_32x32x16_bf16 v[16:31], v[232:235], v[244:247], v[16:31]
	v_mfma_f32_32x32x16_bf16 v[0:15], v[232:235], v[248:251], v[0:15]
	s_add_u32 s101, s101, 2
	s_branch .Lgb_loop
